# rmsnorm row loop software-pipelined by one row (next row's loads in flight during the current row's reduction and stores)
# speedup vs baseline: 1.0094x; 1.0094x over previous
.LBB0_290:
	s_mov_b64 s[10:11], 0
	v_mov_b64_e32 v[60:61], v[38:39]
	v_lshl_add_u64 v[8:9], v[40:41], 0, s[10:11]
	global_load_dwordx4 v[30:33], v[8:9], off
	global_load_dwordx4 v[4:7], v[8:9], off offset:1024
	global_load_dwordx4 v[0:3], v[8:9], off offset:3072
	global_load_dwordx4 v[8:11], v[8:9], off offset:2048
.Lnrm_loop:
	s_add_u32 s4, s10, 0x1000
	s_addc_u32 s5, s11, 0
	v_lshl_add_u64 v[94:95], v[40:41], 0, s[4:5]
	global_load_dwordx4 v[98:101], v[94:95], off
	global_load_dwordx4 v[90:93], v[94:95], off offset:1024
	global_load_dwordx4 v[86:89], v[94:95], off offset:3072
	global_load_dwordx4 v[94:97], v[94:95], off offset:2048
	s_waitcnt vmcnt(4)
	s_mov_b64 s[12:13], -1
	s_and_b64 vcc, exec, s[0:1]
	v_pk_mul_f32 v[62:63], v[32:33], v[32:33]
	v_pk_mul_f32 v[64:65], v[30:31], v[30:31]
	v_pk_mul_f32 v[74:75], v[6:7], v[6:7]
	v_pk_mul_f32 v[76:77], v[4:5], v[4:5]
	v_pk_mov_b32 v[80:81], v[64:65], v[62:63] op_sel:[1,0]
	v_mov_b32_e32 v65, v63
	v_pk_mov_b32 v[62:63], v[76:77], v[74:75] op_sel:[1,0]
	v_mov_b32_e32 v77, v75
	v_mul_f32_e32 v12, v9, v9
	v_mul_f32_e32 v78, v11, v11
	v_pk_add_f32 v[64:65], v[80:81], v[64:65]
	v_pk_add_f32 v[62:63], v[62:63], v[76:77]
	v_mul_f32_e32 v82, v0, v0
	v_mul_f32_e32 v83, v1, v1
	v_mul_f32_e32 v84, v2, v2
	v_mul_f32_e32 v85, v3, v3
	v_pk_fma_f32 v[74:75], v[8:9], v[8:9], v[12:13] op_sel_hi:[1,1,0]
	v_pk_fma_f32 v[78:79], v[10:11], v[10:11], v[78:79] op_sel_hi:[1,1,0]
	v_pk_add_f32 v[64:65], v[64:65], v[64:65] op_sel:[0,1] op_sel_hi:[1,0]
	v_pk_add_f32 v[62:63], v[62:63], v[62:63] op_sel:[0,1] op_sel_hi:[1,0]
	v_mov_b32_e32 v75, v84
	v_mov_b32_e32 v79, v85
	v_mov_b32_e32 v65, v82
	v_mov_b32_e32 v63, v83
	v_pk_add_f32 v[74:75], v[74:75], v[78:79]
	v_pk_add_f32 v[62:63], v[64:65], v[62:63]
	s_nop 0
	v_pk_add_f32 v[62:63], v[62:63], v[74:75]
	s_nop 0
	v_add_f32_e32 v12, v62, v63
	ds_bpermute_b32 v62, v35, v12
	s_waitcnt lgkmcnt(0)
	v_add_f32_e32 v12, v12, v62
	ds_bpermute_b32 v62, v66, v12
	s_waitcnt lgkmcnt(0)
	v_add_f32_e32 v12, v12, v62
	ds_bpermute_b32 v62, v67, v12
	s_waitcnt lgkmcnt(0)
	v_add_f32_e32 v12, v12, v62
	ds_bpermute_b32 v62, v68, v12
	s_waitcnt lgkmcnt(0)
	v_add_f32_e32 v12, v12, v62
	ds_bpermute_b32 v62, v69, v12
	s_waitcnt lgkmcnt(0)
	v_add_f32_e32 v12, v12, v62
	ds_bpermute_b32 v62, v70, v12
	s_waitcnt lgkmcnt(0)
	v_add_f32_e32 v12, v12, v62
	v_fmamk_f32 v12, v12, 0x3a800000, v166
	v_mul_f32_e32 v62, 0x4b800000, v12
	v_cmp_gt_f32_e64 s[4:5], s29, v12
	s_nop 1
	v_cndmask_b32_e64 v12, v12, v62, s[4:5]
	v_rsq_f32_e32 v12, v12
	s_nop 0
	v_mul_f32_e32 v62, 0x45800000, v12
	v_cndmask_b32_e64 v62, v12, v62, s[4:5]
	v_mov_b32_e32 v63, v62
	v_pk_mul_f32 v[64:65], v[62:63], v[30:31]
	v_pk_mul_f32 v[30:31], v[62:63], v[4:5]
	v_pk_mul_f32 v[4:5], v[62:63], v[8:9]
	v_pk_mul_f32 v[0:1], v[62:63], v[0:1]
	s_cbranch_vccnz .Lnrm_f_a
	v_mov_b32_e32 v63, v62
	v_pk_mul_f32 v[8:9], v[62:63], v[32:33]
	v_pk_fma_f32 v[74:75], v[44:45], v[64:65], v[14:15]
	v_pk_fma_f32 v[8:9], v[46:47], v[8:9], v[16:17]
	v_cvt_pk_bf16_f32 v74, v74, v75
	v_cvt_pk_bf16_f32 v75, v8, v9
	v_pk_mul_f32 v[8:9], v[62:63], v[6:7]
	global_store_dwordx2 v[60:61], v[74:75], off offset:-1024
	v_pk_fma_f32 v[8:9], v[50:51], v[8:9], v[20:21]
	v_pk_fma_f32 v[74:75], v[48:49], v[30:31], v[18:19]
	s_mov_b64 s[12:13], 0
	v_cvt_pk_bf16_f32 v74, v74, v75
	v_cvt_pk_bf16_f32 v75, v8, v9
	v_pk_mul_f32 v[8:9], v[62:63], v[10:11]
	global_store_dwordx2 v[60:61], v[74:75], off offset:-512
	v_pk_fma_f32 v[8:9], v[54:55], v[8:9], v[24:25]
	v_pk_fma_f32 v[74:75], v[52:53], v[4:5], v[22:23]
	s_nop 0
	v_cvt_pk_bf16_f32 v74, v74, v75
	v_cvt_pk_bf16_f32 v75, v8, v9
	v_pk_mul_f32 v[8:9], v[62:63], v[2:3]
	global_store_dwordx2 v[60:61], v[74:75], off
	v_pk_fma_f32 v[8:9], v[58:59], v[8:9], v[28:29]
	v_pk_fma_f32 v[74:75], v[56:57], v[0:1], v[26:27]
	s_nop 0
	v_cvt_pk_bf16_f32 v74, v74, v75
	v_cvt_pk_bf16_f32 v75, v8, v9
	global_store_dwordx2 v[60:61], v[74:75], off offset:512

.Lnrm_d_a:
	v_lshl_add_u64 v[60:61], v[60:61], 0, s[36:37]
	s_add_u32 s10, s10, 0x1000
	s_addc_u32 s11, s11, 0
	s_add_u32 s4, s10, 0x1000
	s_addc_u32 s5, s11, 0
	s_cmp_eq_u32 s4, 0x10000
	s_cbranch_scc1 .Lnrm_nopf
	v_lshl_add_u64 v[8:9], v[40:41], 0, s[4:5]
	global_load_dwordx4 v[30:33], v[8:9], off
	global_load_dwordx4 v[4:7], v[8:9], off offset:1024
	global_load_dwordx4 v[0:3], v[8:9], off offset:3072
	global_load_dwordx4 v[8:11], v[8:9], off offset:2048
.Lnrm_nopf:
	s_waitcnt vmcnt(4)
	s_mov_b64 s[12:13], -1
	s_and_b64 vcc, exec, s[0:1]
	v_pk_mul_f32 v[62:63], v[100:101], v[100:101]
	v_pk_mul_f32 v[64:65], v[98:99], v[98:99]
	v_pk_mul_f32 v[74:75], v[92:93], v[92:93]
	v_pk_mul_f32 v[76:77], v[90:91], v[90:91]
	v_pk_mov_b32 v[80:81], v[64:65], v[62:63] op_sel:[1,0]
	v_mov_b32_e32 v65, v63
	v_pk_mov_b32 v[62:63], v[76:77], v[74:75] op_sel:[1,0]
	v_mov_b32_e32 v77, v75
	v_mul_f32_e32 v12, v95, v95
	v_mul_f32_e32 v78, v97, v97
	v_pk_add_f32 v[64:65], v[80:81], v[64:65]
	v_pk_add_f32 v[62:63], v[62:63], v[76:77]
	v_mul_f32_e32 v82, v86, v86
	v_mul_f32_e32 v83, v87, v87
	v_mul_f32_e32 v84, v88, v88
	v_mul_f32_e32 v85, v89, v89
	v_pk_fma_f32 v[74:75], v[94:95], v[94:95], v[12:13] op_sel_hi:[1,1,0]
	v_pk_fma_f32 v[78:79], v[96:97], v[96:97], v[78:79] op_sel_hi:[1,1,0]
	v_pk_add_f32 v[64:65], v[64:65], v[64:65] op_sel:[0,1] op_sel_hi:[1,0]
	v_pk_add_f32 v[62:63], v[62:63], v[62:63] op_sel:[0,1] op_sel_hi:[1,0]
	v_mov_b32_e32 v75, v84
	v_mov_b32_e32 v79, v85
	v_mov_b32_e32 v65, v82
	v_mov_b32_e32 v63, v83
	v_pk_add_f32 v[74:75], v[74:75], v[78:79]
	v_pk_add_f32 v[62:63], v[64:65], v[62:63]
	s_nop 0
	v_pk_add_f32 v[62:63], v[62:63], v[74:75]
	s_nop 0
	v_add_f32_e32 v12, v62, v63
	ds_bpermute_b32 v62, v35, v12
	s_waitcnt lgkmcnt(0)
	v_add_f32_e32 v12, v12, v62
	ds_bpermute_b32 v62, v66, v12
	s_waitcnt lgkmcnt(0)
	v_add_f32_e32 v12, v12, v62
	ds_bpermute_b32 v62, v67, v12
	s_waitcnt lgkmcnt(0)
	v_add_f32_e32 v12, v12, v62
	ds_bpermute_b32 v62, v68, v12
	s_waitcnt lgkmcnt(0)
	v_add_f32_e32 v12, v12, v62
	ds_bpermute_b32 v62, v69, v12
	s_waitcnt lgkmcnt(0)
	v_add_f32_e32 v12, v12, v62
	ds_bpermute_b32 v62, v70, v12
	s_waitcnt lgkmcnt(0)
	v_add_f32_e32 v12, v12, v62
	v_fmamk_f32 v12, v12, 0x3a800000, v166
	v_mul_f32_e32 v62, 0x4b800000, v12
	v_cmp_gt_f32_e64 s[4:5], s29, v12
	s_nop 1
	v_cndmask_b32_e64 v12, v12, v62, s[4:5]
	v_rsq_f32_e32 v12, v12
	s_nop 0
	v_mul_f32_e32 v62, 0x45800000, v12
	v_cndmask_b32_e64 v62, v12, v62, s[4:5]
	v_mov_b32_e32 v63, v62
	v_pk_mul_f32 v[64:65], v[62:63], v[98:99]
	v_pk_mul_f32 v[98:99], v[62:63], v[90:91]
	v_pk_mul_f32 v[90:91], v[62:63], v[94:95]
	v_pk_mul_f32 v[86:87], v[62:63], v[86:87]
	s_cbranch_vccnz .Lnrm_f_b
	v_mov_b32_e32 v63, v62
	v_pk_mul_f32 v[94:95], v[62:63], v[100:101]
	v_pk_fma_f32 v[74:75], v[44:45], v[64:65], v[14:15]
	v_pk_fma_f32 v[94:95], v[46:47], v[94:95], v[16:17]
	v_cvt_pk_bf16_f32 v74, v74, v75
	v_cvt_pk_bf16_f32 v75, v94, v95
	v_pk_mul_f32 v[94:95], v[62:63], v[92:93]
	global_store_dwordx2 v[60:61], v[74:75], off offset:-1024
	v_pk_fma_f32 v[94:95], v[50:51], v[94:95], v[20:21]
	v_pk_fma_f32 v[74:75], v[48:49], v[98:99], v[18:19]
	s_mov_b64 s[12:13], 0
	v_cvt_pk_bf16_f32 v74, v74, v75
	v_cvt_pk_bf16_f32 v75, v94, v95
	v_pk_mul_f32 v[94:95], v[62:63], v[96:97]
	global_store_dwordx2 v[60:61], v[74:75], off offset:-512
	v_pk_fma_f32 v[94:95], v[54:55], v[94:95], v[24:25]
	v_pk_fma_f32 v[74:75], v[52:53], v[90:91], v[22:23]
	s_nop 0
	v_cvt_pk_bf16_f32 v74, v74, v75
	v_cvt_pk_bf16_f32 v75, v94, v95
	v_pk_mul_f32 v[94:95], v[62:63], v[88:89]
	global_store_dwordx2 v[60:61], v[74:75], off
	v_pk_fma_f32 v[94:95], v[58:59], v[94:95], v[28:29]
	v_pk_fma_f32 v[74:75], v[56:57], v[86:87], v[26:27]
	s_nop 0
	v_cvt_pk_bf16_f32 v74, v74, v75
	v_cvt_pk_bf16_f32 v75, v94, v95
	global_store_dwordx2 v[60:61], v[74:75], off offset:512
.Lnrm_f_b:
	s_andn2_b64 vcc, exec, s[12:13]
	s_cbranch_vccnz .Lnrm_d_b
	v_mov_b32_e32 v63, v62
	v_pk_mul_f32 v[94:95], v[62:63], v[100:101]
	v_pk_mul_f32 v[92:93], v[62:63], v[92:93]
	v_lshl_add_u64 v[78:79], v[42:43], 0, s[10:11]
	v_pk_mul_f32 v[76:77], v[46:47], v[94:95]
	v_pk_mul_f32 v[94:95], v[50:51], v[92:93]
	v_pk_mul_f32 v[92:93], v[48:49], v[98:99]
	global_store_dwordx4 v[78:79], v[92:95], off offset:1024
	v_pk_mul_f32 v[88:89], v[62:63], v[88:89]
	v_pk_mul_f32 v[74:75], v[44:45], v[64:65]
	v_pk_mul_f32 v[92:93], v[62:63], v[96:97]
	v_pk_mul_f32 v[90:91], v[52:53], v[90:91]
	v_pk_mul_f32 v[92:93], v[54:55], v[92:93]
	v_pk_mul_f32 v[88:89], v[58:59], v[88:89]
	v_pk_mul_f32 v[86:87], v[56:57], v[86:87]
	global_store_dwordx4 v[78:79], v[74:77], off
	global_store_dwordx4 v[78:79], v[90:93], off offset:2048
	global_store_dwordx4 v[78:79], v[86:89], off offset:3072
.Lnrm_d_b:
	v_lshl_add_u64 v[60:61], v[60:61], 0, s[36:37]
	s_add_u32 s10, s10, 0x1000
	s_addc_u32 s11, s11, 0
	s_cmp_eq_u32 s10, 0x10000
	s_cbranch_scc0 .Lnrm_loop
	s_branch .LBB0_273
